# FFN-up epilogue: a wave's two column tiles adjacent in memory, half-wave swap (v_permlane32_swap) and whole 128-byte line stores (64 instead of 128 store instructions per wave and macro-tile)
# baseline (speedup 1.0000x reference)
.LBB0_2769:
	v_readlane_b32 s2, v246, 26
	s_cmp_eq_u32 s2, 10
	s_cselect_b64 s[8:9], -1, 0
	s_load_dwordx2 s[10:11], s[0:1], 0x108
	v_cndmask_b32_e64 v0, 0, 1, s[8:9]
	s_mov_b32 s2, s83
	v_readfirstlane_b32 s0, v0
	s_or_b32 s0, s58, s0
	s_mul_hi_i32 s1, s0, 0xb00000
	s_mul_i32 s0, s0, 0xb00000
	s_waitcnt lgkmcnt(0)
	s_add_u32 s0, s10, s0
	s_addc_u32 s1, s11, s1
	s_add_u32 s0, s0, 0x7c78100
	s_addc_u32 s1, s1, 0
	s_add_u32 s8, s10, 0x3000000
	s_addc_u32 s9, s11, 0
	s_add_u32 s10, s10, 0x14958100
	s_addc_u32 s11, s11, 0
	s_mov_b32 s14, 0x10000
	v_and_b32_e32 v171, 63, v194
	v_lshrrev_b32_e32 v172, 6, v194
	v_lshrrev_b32_e32 v160, 2, v194
	v_lshlrev_b32_e32 v160, 11, v160
	v_and_b32_e32 v173, 3, v171
	v_bfe_u32 v174, v171, 4, 2
	v_xor_b32_e32 v173, v173, v174
	v_lshl_add_u32 v160, v173, 4, v160
	v_add_u32_e32 v161, 0x20000, v160
	v_and_b32_e32 v175, 31, v171
	v_lshrrev_b32_e32 v176, 5, v171
	v_bfe_u32 v177, v175, 2, 2
	v_xor_b32_e32 v178, v176, v177
	v_xor_b32_e32 v179, 2, v178
	v_lshrrev_b32_e32 v180, 1, v172
	v_and_b32_e32 v181, 1, v172
	v_lshl_add_u32 v182, v180, 6, v175
	v_lshl_add_u32 v183, v181, 6, v175
	v_lshlrev_b32_e32 v182, 6, v182
	v_lshlrev_b32_e32 v183, 6, v183
	v_lshl_add_u32 v154, v178, 4, v182
	v_lshl_add_u32 v155, v179, 4, v182
	v_lshl_add_u32 v156, v178, 4, v183
	v_lshl_add_u32 v157, v179, 4, v183
	v_add_u32_e32 v158, 0x2000, v156
	v_add_u32_e32 v159, 0x2000, v157
	v_lshlrev_b32_e32 v184, 6, v180
	v_lshl_add_u32 v184, v176, 2, v184
	v_mul_u32_u24_e32 v184, 0x1600, v184
	v_lshl_add_u32 v185, v181, 5, v175
	v_lshl_add_u32 v162, v185, 1, v184
	v_add_u32_e32 v163, 0x1600, v162
	v_add_u32_e32 v164, 0x2c00, v162
	v_add_u32_e32 v165, 0x4200, v162
	v_lshrrev_b32_e32 v173, 3, v171
	v_lshl_add_u32 v173, v172, 3, v173
	v_lshlrev_b32_e32 v173, 11, v173
	v_and_b32_e32 v174, 1, v172
	v_lshrrev_b32_e32 v177, 4, v171
	v_lshl_add_u32 v174, v174, 2, v177
	v_and_b32_e32 v177, 7, v171
	v_xor_b32_e32 v174, v174, v177
	v_lshl_add_u32 v249, v174, 4, v173
	v_add_u32_e32 v254, 0x20000, v249
	v_add_u32_e32 v166, 0x10000, v249
	v_add_u32_e32 v167, 0x30000, v249
	v_add_u32_e32 v255, 0x40000, v249
	v_add_u32_e32 v250, 0x50000, v249
	v_mul_u32_u24_e32 v251, 0x58000, v180
	v_lshl_add_u32 v173, v181, 6, v171
	v_lshl_add_u32 v251, v173, 1, v251
	v_bfe_u32 v177, v175, 1, 3
	v_or_b32_e32 v174, 0, v176
	v_xor_b32_e32 v174, v174, v177
	v_lshlrev_b32_e32 v174, 4, v174
	v_lshl_add_u32 v173, v180, 5, v175
	v_lshl_add_u32 v168, v173, 7, v174
	v_lshl_add_u32 v173, v181, 5, v175
	v_lshl_add_u32 v238, v173, 7, v174
	v_add_u32_e32 v242, 0x4000, v238
	v_or_b32_e32 v174, 4, v176
	v_xor_b32_e32 v174, v174, v177
	v_lshlrev_b32_e32 v174, 4, v174
	v_lshl_add_u32 v173, v180, 5, v175
	v_lshl_add_u32 v169, v173, 7, v174
	v_lshl_add_u32 v173, v181, 5, v175
	v_lshl_add_u32 v239, v173, 7, v174
	v_add_u32_e32 v243, 0x4000, v239
	v_or_b32_e32 v174, 2, v176
	v_xor_b32_e32 v174, v174, v177
	v_lshlrev_b32_e32 v174, 4, v174
	v_lshl_add_u32 v173, v180, 5, v175
	v_lshl_add_u32 v236, v173, 7, v174
	v_lshl_add_u32 v173, v181, 5, v175
	v_lshl_add_u32 v240, v173, 7, v174
	v_add_u32_e32 v244, 0x4000, v240
	v_or_b32_e32 v174, 6, v176
	v_xor_b32_e32 v174, v174, v177
	v_lshlrev_b32_e32 v174, 4, v174
	v_lshl_add_u32 v173, v180, 5, v175
	v_lshl_add_u32 v237, v173, 7, v174
	v_lshl_add_u32 v173, v181, 5, v175
	v_lshl_add_u32 v241, v173, 7, v174
	v_add_u32_e32 v245, 0x4000, v241
	v_readfirstlane_b32 s65, v194
	s_nop 0
	s_lshl_b32 s65, s65, 4
	s_add_u32 s65, s65, 16
	v_readlane_b32 s62, v246, 14
	s_mov_b32 s64, 0

.Lhw_ffnup_dloop:
	s_cmp_ge_u32 s2, s64
	s_cbranch_scc1 .Lhw_ffnup_tail
	s_mul_i32 s6, s2, 745
	s_lshr_b32 s6, s6, 16
	s_mul_i32 s14, s6, 88
	s_sub_i32 s14, s2, s14
	v_readlane_b32 s13, v246, 16
	s_lshl_b32 s6, s6, 2
	s_and_b32 s12, s14, 3
	s_add_i32 s6, s6, s12
	s_add_i32 s6, s6, s13
	s_lshl_b32 s6, s6, 7
	s_lshr_b32 s14, s14, 2
	s_lshl_b32 s14, s14, 8
	s_lshl_b32 vcc_lo, s6, 11
	s_add_u32 s66, s10, vcc_lo
	s_addc_u32 s67, s11, 0
	s_lshl_b32 vcc_lo, s14, 11
	s_add_u32 s12, s0, vcc_lo
	s_addc_u32 s13, s1, 0
	s_add_u32 s62, s12, 0x20000
	s_addc_u32 s63, s13, 0
	s_barrier
	s_sub_u32 s66, s66, 64
	s_subb_u32 s67, s67, 0
	s_sub_u32 s12, s12, 64
	s_subb_u32 s13, s13, 0
	s_sub_u32 s62, s62, 64
	s_subb_u32 s63, s63, 0
	s_add_u32 m0, s65, 0x0
	s_nop 0
	global_load_lds_dwordx4 v166, s[66:67]
	s_add_u32 m0, s65, 0x1000
	s_nop 0
	global_load_lds_dwordx4 v167, s[66:67]
	s_add_u32 m0, s65, 0x2000
	s_nop 0
	global_load_lds_dwordx4 v166, s[12:13]
	s_add_u32 m0, s65, 0x3000
	s_nop 0
	global_load_lds_dwordx4 v250, s[12:13]
	s_add_u32 m0, s65, 0x4000
	s_nop 0
	global_load_lds_dwordx4 v166, s[62:63]
	s_add_u32 m0, s65, 0x5000
	s_nop 0
	global_load_lds_dwordx4 v250, s[62:63]
	s_add_u32 s66, s66, 64
	s_addc_u32 s67, s67, 0
	s_add_u32 s12, s12, 64
	s_addc_u32 s13, s13, 0
	s_add_u32 s62, s62, 64
	s_addc_u32 s63, s63, 0
	s_add_u32 m0, s65, 0x6000
	s_nop 0
	global_load_lds_dwordx4 v249, s[66:67]
	s_add_u32 m0, s65, 0x7000
	s_nop 0
	global_load_lds_dwordx4 v254, s[66:67]
	s_add_u32 m0, s65, 0x8000
	s_nop 0
	global_load_lds_dwordx4 v249, s[12:13]
	s_add_u32 m0, s65, 0x9000
	s_nop 0
	global_load_lds_dwordx4 v255, s[12:13]
	s_add_u32 m0, s65, 0xa000
	s_nop 0
	global_load_lds_dwordx4 v249, s[62:63]
	s_add_u32 m0, s65, 0xb000
	s_nop 0
	global_load_lds_dwordx4 v255, s[62:63]
	s_add_u32 s66, s66, 64
	s_addc_u32 s67, s67, 0
	s_add_u32 s12, s12, 64
	s_addc_u32 s13, s13, 0
	s_add_u32 s62, s62, 64
	s_addc_u32 s63, s63, 0
	s_add_u32 m0, s65, 0xc000
	s_nop 0
	global_load_lds_dwordx4 v166, s[66:67]
	s_add_u32 m0, s65, 0xd000
	s_nop 0
	global_load_lds_dwordx4 v167, s[66:67]
	s_add_u32 m0, s65, 0xe000
	s_nop 0
	global_load_lds_dwordx4 v166, s[12:13]
	s_add_u32 m0, s65, 0xf000
	s_nop 0
	global_load_lds_dwordx4 v250, s[12:13]
	s_add_u32 m0, s65, 0x10000
	s_nop 0
	global_load_lds_dwordx4 v166, s[62:63]
	s_add_u32 m0, s65, 0x11000
	s_nop 0
	global_load_lds_dwordx4 v250, s[62:63]
	s_add_u32 s66, s66, 64
	s_addc_u32 s67, s67, 0
	s_add_u32 s12, s12, 64
	s_addc_u32 s13, s13, 0
	s_add_u32 s62, s62, 64
	s_addc_u32 s63, s63, 0
	v_mov_b32_e32 v2, 0
	v_mov_b32_e32 v3, 0
	v_mov_b32_e32 v4, 0
	v_mov_b32_e32 v5, 0
	v_mov_b32_e32 v6, 0
	v_mov_b32_e32 v7, 0
	v_mov_b32_e32 v8, 0
	v_mov_b32_e32 v9, 0
	v_mov_b32_e32 v10, 0
	v_mov_b32_e32 v11, 0
	v_mov_b32_e32 v12, 0
	v_mov_b32_e32 v13, 0
	v_mov_b32_e32 v14, 0
	v_mov_b32_e32 v15, 0
	v_mov_b32_e32 v16, 0
	v_mov_b32_e32 v17, 0
	v_mov_b32_e32 v18, 0
	v_mov_b32_e32 v19, 0
	v_mov_b32_e32 v20, 0
	v_mov_b32_e32 v21, 0
	v_mov_b32_e32 v22, 0
	v_mov_b32_e32 v23, 0
	v_mov_b32_e32 v24, 0
	v_mov_b32_e32 v25, 0
	v_mov_b32_e32 v26, 0
	v_mov_b32_e32 v27, 0
	v_mov_b32_e32 v28, 0
	v_mov_b32_e32 v29, 0
	v_mov_b32_e32 v30, 0
	v_mov_b32_e32 v31, 0
	v_mov_b32_e32 v32, 0
	v_mov_b32_e32 v33, 0
	v_mov_b32_e32 v34, 0
	v_mov_b32_e32 v35, 0
	v_mov_b32_e32 v36, 0
	v_mov_b32_e32 v37, 0
	v_mov_b32_e32 v38, 0
	v_mov_b32_e32 v39, 0
	v_mov_b32_e32 v40, 0
	v_mov_b32_e32 v41, 0
	v_mov_b32_e32 v42, 0
	v_mov_b32_e32 v43, 0
	v_mov_b32_e32 v44, 0
	v_mov_b32_e32 v45, 0
	v_mov_b32_e32 v46, 0
	v_mov_b32_e32 v47, 0
	v_mov_b32_e32 v48, 0
	v_mov_b32_e32 v49, 0
	v_mov_b32_e32 v50, 0
	v_mov_b32_e32 v51, 0
	v_mov_b32_e32 v52, 0
	v_mov_b32_e32 v53, 0
	v_mov_b32_e32 v54, 0
	v_mov_b32_e32 v55, 0
	v_mov_b32_e32 v56, 0
	v_mov_b32_e32 v57, 0
	v_mov_b32_e32 v58, 0
	v_mov_b32_e32 v59, 0
	v_mov_b32_e32 v60, 0
	v_mov_b32_e32 v61, 0
	v_mov_b32_e32 v62, 0
	v_mov_b32_e32 v63, 0
	v_mov_b32_e32 v64, 0
	v_mov_b32_e32 v65, 0
	v_mov_b32_e32 v66, 0
	v_mov_b32_e32 v67, 0
	v_mov_b32_e32 v68, 0
	v_mov_b32_e32 v69, 0
	v_mov_b32_e32 v70, 0
	v_mov_b32_e32 v71, 0
	v_mov_b32_e32 v72, 0
	v_mov_b32_e32 v73, 0
	v_mov_b32_e32 v74, 0
	v_mov_b32_e32 v75, 0
	v_mov_b32_e32 v76, 0
	v_mov_b32_e32 v77, 0
	v_mov_b32_e32 v78, 0
	v_mov_b32_e32 v79, 0
	v_mov_b32_e32 v80, 0
	v_mov_b32_e32 v81, 0
	v_mov_b32_e32 v82, 0
	v_mov_b32_e32 v83, 0
	v_mov_b32_e32 v84, 0
	v_mov_b32_e32 v85, 0
	v_mov_b32_e32 v86, 0
	v_mov_b32_e32 v87, 0
	v_mov_b32_e32 v88, 0
	v_mov_b32_e32 v89, 0
	v_mov_b32_e32 v90, 0
	v_mov_b32_e32 v91, 0
	v_mov_b32_e32 v92, 0
	v_mov_b32_e32 v93, 0
	v_mov_b32_e32 v94, 0
	v_mov_b32_e32 v95, 0
	v_mov_b32_e32 v96, 0
	v_mov_b32_e32 v97, 0
	v_mov_b32_e32 v98, 0
	v_mov_b32_e32 v99, 0
	v_mov_b32_e32 v100, 0
	v_mov_b32_e32 v101, 0
	v_mov_b32_e32 v102, 0
	v_mov_b32_e32 v103, 0
	v_mov_b32_e32 v104, 0
	v_mov_b32_e32 v105, 0
	v_mov_b32_e32 v106, 0
	v_mov_b32_e32 v107, 0
	v_mov_b32_e32 v108, 0
	v_mov_b32_e32 v109, 0
	v_mov_b32_e32 v110, 0
	v_mov_b32_e32 v111, 0
	v_mov_b32_e32 v112, 0
	v_mov_b32_e32 v113, 0
	v_mov_b32_e32 v114, 0
	v_mov_b32_e32 v115, 0
	v_mov_b32_e32 v116, 0
	v_mov_b32_e32 v117, 0
	v_mov_b32_e32 v118, 0
	v_mov_b32_e32 v119, 0
	v_mov_b32_e32 v120, 0
	v_mov_b32_e32 v121, 0
	v_mov_b32_e32 v122, 0
	v_mov_b32_e32 v123, 0
	v_mov_b32_e32 v124, 0
	v_mov_b32_e32 v125, 0
	v_mov_b32_e32 v126, 0
	v_mov_b32_e32 v127, 0
	v_mov_b32_e32 v128, 0
	v_mov_b32_e32 v129, 0
	s_waitcnt vmcnt(6)
	s_barrier
	ds_read_b128 v[130:133], v168 offset:24592
	ds_read_b128 v[138:141], v238 offset:32784
	ds_read_b128 v[146:149], v242 offset:24592
	ds_read_b128 v[134:137], v169 offset:16
	ds_read_b128 v[142:145], v239 offset:8208
	ds_read_b128 v[150:153], v243 offset:16
	s_mov_b32 s59, 5
.Lhw_ffnup_d_loop:
	s_waitcnt lgkmcnt(4)
	v_mfma_f32_32x32x16_bf16 v[2:17], v[130:133], v[138:141], v[2:17]
	ds_read_b128 v[212:215], v236 offset:24592
	s_waitcnt lgkmcnt(2)
	v_mfma_f32_32x32x16_bf16 v[18:33], v[130:133], v[142:145], v[18:33]
	ds_read_b128 v[220:223], v240 offset:32784
	v_mfma_f32_32x32x16_bf16 v[34:49], v[134:137], v[138:141], v[34:49]
	ds_read_b128 v[228:231], v244 offset:24592
	v_mfma_f32_32x32x16_bf16 v[50:65], v[134:137], v[142:145], v[50:65]
	ds_read_b128 v[216:219], v237 offset:16
	v_mfma_f32_32x32x16_bf16 v[66:81], v[130:133], v[146:149], v[66:81]
	ds_read_b128 v[224:227], v241 offset:8208
	s_waitcnt lgkmcnt(5)
	v_mfma_f32_32x32x16_bf16 v[82:97], v[130:133], v[150:153], v[82:97]
	ds_read_b128 v[232:235], v245 offset:16
	v_mfma_f32_32x32x16_bf16 v[98:113], v[134:137], v[146:149], v[98:113]
	v_mfma_f32_32x32x16_bf16 v[114:129], v[134:137], v[150:153], v[114:129]
	s_waitcnt vmcnt(0) lgkmcnt(0)
	s_barrier
	v_mfma_f32_32x32x16_bf16 v[2:17], v[212:215], v[220:223], v[2:17]
	s_add_u32 m0, s65, 0x0
	ds_read_b128 v[130:133], v169 offset:24592
	global_load_lds_dwordx4 v249, s[66:67]
	v_mfma_f32_32x32x16_bf16 v[18:33], v[212:215], v[224:227], v[18:33]
	s_add_u32 m0, s65, 0x1000
	ds_read_b128 v[138:141], v239 offset:32784
	global_load_lds_dwordx4 v254, s[66:67]
	v_mfma_f32_32x32x16_bf16 v[34:49], v[216:219], v[220:223], v[34:49]
	s_add_u32 m0, s65, 0x2000
	ds_read_b128 v[146:149], v243 offset:24592
	global_load_lds_dwordx4 v249, s[12:13]
	v_mfma_f32_32x32x16_bf16 v[50:65], v[216:219], v[224:227], v[50:65]
	s_add_u32 m0, s65, 0x3000
	ds_read_b128 v[134:137], v168 offset:49168
	global_load_lds_dwordx4 v255, s[12:13]
	v_mfma_f32_32x32x16_bf16 v[66:81], v[212:215], v[228:231], v[66:81]
	s_add_u32 m0, s65, 0x4000
	ds_read_b128 v[142:145], v238 offset:57360
	global_load_lds_dwordx4 v249, s[62:63]
	v_mfma_f32_32x32x16_bf16 v[82:97], v[212:215], v[232:235], v[82:97]
	s_add_u32 m0, s65, 0x5000
	ds_read_b128 v[150:153], v242 offset:49168
	global_load_lds_dwordx4 v255, s[62:63]
	v_mfma_f32_32x32x16_bf16 v[98:113], v[216:219], v[228:231], v[98:113]
	s_add_u32 s66, s66, 64
	s_addc_u32 s67, s67, 0
	s_add_u32 s12, s12, 64
	s_addc_u32 s13, s13, 0
	v_mfma_f32_32x32x16_bf16 v[114:129], v[216:219], v[232:235], v[114:129]
	s_add_u32 s62, s62, 64
	s_addc_u32 s63, s63, 0
	s_waitcnt lgkmcnt(4)
	v_mfma_f32_32x32x16_bf16 v[2:17], v[130:133], v[138:141], v[2:17]
	ds_read_b128 v[212:215], v237 offset:24592
	s_waitcnt lgkmcnt(2)
	v_mfma_f32_32x32x16_bf16 v[18:33], v[130:133], v[142:145], v[18:33]
	ds_read_b128 v[220:223], v241 offset:32784
	v_mfma_f32_32x32x16_bf16 v[34:49], v[134:137], v[138:141], v[34:49]
	ds_read_b128 v[228:231], v245 offset:24592
	v_mfma_f32_32x32x16_bf16 v[50:65], v[134:137], v[142:145], v[50:65]
	ds_read_b128 v[216:219], v236 offset:49168
	v_mfma_f32_32x32x16_bf16 v[66:81], v[130:133], v[146:149], v[66:81]
	ds_read_b128 v[224:227], v240 offset:57360
	s_waitcnt lgkmcnt(5)
	v_mfma_f32_32x32x16_bf16 v[82:97], v[130:133], v[150:153], v[82:97]
	ds_read_b128 v[232:235], v244 offset:49168
	v_mfma_f32_32x32x16_bf16 v[98:113], v[134:137], v[146:149], v[98:113]
	v_mfma_f32_32x32x16_bf16 v[114:129], v[134:137], v[150:153], v[114:129]
	s_waitcnt vmcnt(0) lgkmcnt(0)
	s_barrier
	v_mfma_f32_32x32x16_bf16 v[2:17], v[212:215], v[220:223], v[2:17]
	s_add_u32 m0, s65, 0x6000
	ds_read_b128 v[130:133], v168 offset:16
	global_load_lds_dwordx4 v166, s[66:67]
	v_mfma_f32_32x32x16_bf16 v[18:33], v[212:215], v[224:227], v[18:33]
	s_add_u32 m0, s65, 0x7000
	ds_read_b128 v[138:141], v238 offset:8208
	global_load_lds_dwordx4 v167, s[66:67]
	v_mfma_f32_32x32x16_bf16 v[34:49], v[216:219], v[220:223], v[34:49]
	s_add_u32 m0, s65, 0x8000
	ds_read_b128 v[146:149], v242 offset:16
	global_load_lds_dwordx4 v166, s[12:13]
	v_mfma_f32_32x32x16_bf16 v[50:65], v[216:219], v[224:227], v[50:65]
	s_add_u32 m0, s65, 0x9000
	ds_read_b128 v[134:137], v169 offset:49168
	global_load_lds_dwordx4 v250, s[12:13]
	v_mfma_f32_32x32x16_bf16 v[66:81], v[212:215], v[228:231], v[66:81]
	s_add_u32 m0, s65, 0xa000
	ds_read_b128 v[142:145], v239 offset:57360
	global_load_lds_dwordx4 v166, s[62:63]
	v_mfma_f32_32x32x16_bf16 v[82:97], v[212:215], v[232:235], v[82:97]
	s_add_u32 m0, s65, 0xb000
	ds_read_b128 v[150:153], v243 offset:49168
	global_load_lds_dwordx4 v250, s[62:63]
	v_mfma_f32_32x32x16_bf16 v[98:113], v[216:219], v[228:231], v[98:113]
	s_add_u32 s66, s66, 64
	s_addc_u32 s67, s67, 0
	s_add_u32 s12, s12, 64
	s_addc_u32 s13, s13, 0
	v_mfma_f32_32x32x16_bf16 v[114:129], v[216:219], v[232:235], v[114:129]
	s_add_u32 s62, s62, 64
	s_addc_u32 s63, s63, 0
	s_waitcnt lgkmcnt(4)
	v_mfma_f32_32x32x16_bf16 v[2:17], v[130:133], v[138:141], v[2:17]
	ds_read_b128 v[212:215], v236 offset:16
	s_waitcnt lgkmcnt(2)
	v_mfma_f32_32x32x16_bf16 v[18:33], v[130:133], v[142:145], v[18:33]
	ds_read_b128 v[220:223], v240 offset:8208
	v_mfma_f32_32x32x16_bf16 v[34:49], v[134:137], v[138:141], v[34:49]
	ds_read_b128 v[228:231], v244 offset:16
	v_mfma_f32_32x32x16_bf16 v[50:65], v[134:137], v[142:145], v[50:65]
	ds_read_b128 v[216:219], v237 offset:49168
	v_mfma_f32_32x32x16_bf16 v[66:81], v[130:133], v[146:149], v[66:81]
	ds_read_b128 v[224:227], v241 offset:57360
	s_waitcnt lgkmcnt(5)
	v_mfma_f32_32x32x16_bf16 v[82:97], v[130:133], v[150:153], v[82:97]
	ds_read_b128 v[232:235], v245 offset:49168
	v_mfma_f32_32x32x16_bf16 v[98:113], v[134:137], v[146:149], v[98:113]
	v_mfma_f32_32x32x16_bf16 v[114:129], v[134:137], v[150:153], v[114:129]
	s_waitcnt vmcnt(0) lgkmcnt(0)
	s_barrier
	v_mfma_f32_32x32x16_bf16 v[2:17], v[212:215], v[220:223], v[2:17]
	s_add_u32 m0, s65, 0xc000
	ds_read_b128 v[130:133], v169 offset:16
	global_load_lds_dwordx4 v249, s[66:67]
	v_mfma_f32_32x32x16_bf16 v[18:33], v[212:215], v[224:227], v[18:33]
	s_add_u32 m0, s65, 0xd000
	ds_read_b128 v[138:141], v239 offset:8208
	global_load_lds_dwordx4 v254, s[66:67]
	v_mfma_f32_32x32x16_bf16 v[34:49], v[216:219], v[220:223], v[34:49]
	s_add_u32 m0, s65, 0xe000
	ds_read_b128 v[146:149], v243 offset:16
	global_load_lds_dwordx4 v249, s[12:13]
	v_mfma_f32_32x32x16_bf16 v[50:65], v[216:219], v[224:227], v[50:65]
	s_add_u32 m0, s65, 0xf000
	ds_read_b128 v[134:137], v168 offset:24592
	global_load_lds_dwordx4 v255, s[12:13]
	v_mfma_f32_32x32x16_bf16 v[66:81], v[212:215], v[228:231], v[66:81]
	s_add_u32 m0, s65, 0x10000
	ds_read_b128 v[142:145], v238 offset:32784
	global_load_lds_dwordx4 v249, s[62:63]
	v_mfma_f32_32x32x16_bf16 v[82:97], v[212:215], v[232:235], v[82:97]
	s_add_u32 m0, s65, 0x11000
	ds_read_b128 v[150:153], v242 offset:24592
	global_load_lds_dwordx4 v255, s[62:63]
	v_mfma_f32_32x32x16_bf16 v[98:113], v[216:219], v[228:231], v[98:113]
	s_add_u32 s66, s66, 64
	s_addc_u32 s67, s67, 0
	s_add_u32 s12, s12, 64
	s_addc_u32 s13, s13, 0
	v_mfma_f32_32x32x16_bf16 v[114:129], v[216:219], v[232:235], v[114:129]
	s_add_u32 s62, s62, 64
	s_addc_u32 s63, s63, 0
	s_waitcnt lgkmcnt(4)
	v_mfma_f32_32x32x16_bf16 v[2:17], v[130:133], v[138:141], v[2:17]
	ds_read_b128 v[212:215], v237 offset:16
	s_waitcnt lgkmcnt(2)
	v_mfma_f32_32x32x16_bf16 v[18:33], v[130:133], v[142:145], v[18:33]
	ds_read_b128 v[220:223], v241 offset:8208
	v_mfma_f32_32x32x16_bf16 v[34:49], v[134:137], v[138:141], v[34:49]
	ds_read_b128 v[228:231], v245 offset:16
	v_mfma_f32_32x32x16_bf16 v[50:65], v[134:137], v[142:145], v[50:65]
	ds_read_b128 v[216:219], v236 offset:24592
	v_mfma_f32_32x32x16_bf16 v[66:81], v[130:133], v[146:149], v[66:81]
	ds_read_b128 v[224:227], v240 offset:32784
	s_waitcnt lgkmcnt(5)
	v_mfma_f32_32x32x16_bf16 v[82:97], v[130:133], v[150:153], v[82:97]
	ds_read_b128 v[232:235], v244 offset:24592
	v_mfma_f32_32x32x16_bf16 v[98:113], v[134:137], v[146:149], v[98:113]
	v_mfma_f32_32x32x16_bf16 v[114:129], v[134:137], v[150:153], v[114:129]
	s_waitcnt vmcnt(0) lgkmcnt(0)
	s_barrier
	v_mfma_f32_32x32x16_bf16 v[2:17], v[212:215], v[220:223], v[2:17]
	s_add_u32 m0, s65, 0x0
	ds_read_b128 v[130:133], v168 offset:49168
	global_load_lds_dwordx4 v166, s[66:67]
	v_mfma_f32_32x32x16_bf16 v[18:33], v[212:215], v[224:227], v[18:33]
	s_add_u32 m0, s65, 0x1000
	ds_read_b128 v[138:141], v238 offset:57360
	global_load_lds_dwordx4 v167, s[66:67]
	v_mfma_f32_32x32x16_bf16 v[34:49], v[216:219], v[220:223], v[34:49]
	s_add_u32 m0, s65, 0x2000
	ds_read_b128 v[146:149], v242 offset:49168
	global_load_lds_dwordx4 v166, s[12:13]
	v_mfma_f32_32x32x16_bf16 v[50:65], v[216:219], v[224:227], v[50:65]
	s_add_u32 m0, s65, 0x3000
	ds_read_b128 v[134:137], v169 offset:24592
	global_load_lds_dwordx4 v250, s[12:13]
	v_mfma_f32_32x32x16_bf16 v[66:81], v[212:215], v[228:231], v[66:81]
	s_add_u32 m0, s65, 0x4000
	ds_read_b128 v[142:145], v239 offset:32784
	global_load_lds_dwordx4 v166, s[62:63]
	v_mfma_f32_32x32x16_bf16 v[82:97], v[212:215], v[232:235], v[82:97]
	s_add_u32 m0, s65, 0x5000
	ds_read_b128 v[150:153], v243 offset:24592
	global_load_lds_dwordx4 v250, s[62:63]
	v_mfma_f32_32x32x16_bf16 v[98:113], v[216:219], v[228:231], v[98:113]
	s_add_u32 s66, s66, 64
	s_addc_u32 s67, s67, 0
	s_add_u32 s12, s12, 64
	s_addc_u32 s13, s13, 0
	v_mfma_f32_32x32x16_bf16 v[114:129], v[216:219], v[232:235], v[114:129]
	s_add_u32 s62, s62, 64
	s_addc_u32 s63, s63, 0
	s_waitcnt lgkmcnt(4)
	v_mfma_f32_32x32x16_bf16 v[2:17], v[130:133], v[138:141], v[2:17]
	ds_read_b128 v[212:215], v236 offset:49168
	s_waitcnt lgkmcnt(2)
	v_mfma_f32_32x32x16_bf16 v[18:33], v[130:133], v[142:145], v[18:33]
	ds_read_b128 v[220:223], v240 offset:57360
	v_mfma_f32_32x32x16_bf16 v[34:49], v[134:137], v[138:141], v[34:49]
	ds_read_b128 v[228:231], v244 offset:49168
	v_mfma_f32_32x32x16_bf16 v[50:65], v[134:137], v[142:145], v[50:65]
	ds_read_b128 v[216:219], v237 offset:24592
	v_mfma_f32_32x32x16_bf16 v[66:81], v[130:133], v[146:149], v[66:81]
	ds_read_b128 v[224:227], v241 offset:32784
	s_waitcnt lgkmcnt(5)
	v_mfma_f32_32x32x16_bf16 v[82:97], v[130:133], v[150:153], v[82:97]
	ds_read_b128 v[232:235], v245 offset:24592
	v_mfma_f32_32x32x16_bf16 v[98:113], v[134:137], v[146:149], v[98:113]
	v_mfma_f32_32x32x16_bf16 v[114:129], v[134:137], v[150:153], v[114:129]
	s_waitcnt vmcnt(0) lgkmcnt(0)
	s_barrier
	v_mfma_f32_32x32x16_bf16 v[2:17], v[212:215], v[220:223], v[2:17]
	s_add_u32 m0, s65, 0x6000
	ds_read_b128 v[130:133], v169 offset:49168
	global_load_lds_dwordx4 v249, s[66:67]
	v_mfma_f32_32x32x16_bf16 v[18:33], v[212:215], v[224:227], v[18:33]
	s_add_u32 m0, s65, 0x7000
	ds_read_b128 v[138:141], v239 offset:57360
	global_load_lds_dwordx4 v254, s[66:67]
	v_mfma_f32_32x32x16_bf16 v[34:49], v[216:219], v[220:223], v[34:49]
	s_add_u32 m0, s65, 0x8000
	ds_read_b128 v[146:149], v243 offset:49168
	global_load_lds_dwordx4 v249, s[12:13]
	v_mfma_f32_32x32x16_bf16 v[50:65], v[216:219], v[224:227], v[50:65]
	s_add_u32 m0, s65, 0x9000
	ds_read_b128 v[134:137], v168 offset:16
	global_load_lds_dwordx4 v255, s[12:13]
	v_mfma_f32_32x32x16_bf16 v[66:81], v[212:215], v[228:231], v[66:81]
	s_add_u32 m0, s65, 0xa000
	ds_read_b128 v[142:145], v238 offset:8208
	global_load_lds_dwordx4 v249, s[62:63]
	v_mfma_f32_32x32x16_bf16 v[82:97], v[212:215], v[232:235], v[82:97]
	s_add_u32 m0, s65, 0xb000
	ds_read_b128 v[150:153], v242 offset:16
	global_load_lds_dwordx4 v255, s[62:63]
	v_mfma_f32_32x32x16_bf16 v[98:113], v[216:219], v[228:231], v[98:113]
	s_add_u32 s66, s66, 64
	s_addc_u32 s67, s67, 0
	s_add_u32 s12, s12, 64
	s_addc_u32 s13, s13, 0
	v_mfma_f32_32x32x16_bf16 v[114:129], v[216:219], v[232:235], v[114:129]
	s_add_u32 s62, s62, 64
	s_addc_u32 s63, s63, 0
	s_waitcnt lgkmcnt(4)
	v_mfma_f32_32x32x16_bf16 v[2:17], v[130:133], v[138:141], v[2:17]
	ds_read_b128 v[212:215], v237 offset:49168
	s_waitcnt lgkmcnt(2)
	v_mfma_f32_32x32x16_bf16 v[18:33], v[130:133], v[142:145], v[18:33]
	ds_read_b128 v[220:223], v241 offset:57360
	v_mfma_f32_32x32x16_bf16 v[34:49], v[134:137], v[138:141], v[34:49]
	ds_read_b128 v[228:231], v245 offset:49168
	v_mfma_f32_32x32x16_bf16 v[50:65], v[134:137], v[142:145], v[50:65]
	ds_read_b128 v[216:219], v236 offset:16
	v_mfma_f32_32x32x16_bf16 v[66:81], v[130:133], v[146:149], v[66:81]
	ds_read_b128 v[224:227], v240 offset:8208
	s_waitcnt lgkmcnt(5)
	v_mfma_f32_32x32x16_bf16 v[82:97], v[130:133], v[150:153], v[82:97]
	ds_read_b128 v[232:235], v244 offset:16
	v_mfma_f32_32x32x16_bf16 v[98:113], v[134:137], v[146:149], v[98:113]
	v_mfma_f32_32x32x16_bf16 v[114:129], v[134:137], v[150:153], v[114:129]
	s_waitcnt vmcnt(0) lgkmcnt(0)
	s_barrier
	v_mfma_f32_32x32x16_bf16 v[2:17], v[212:215], v[220:223], v[2:17]
	s_add_u32 m0, s65, 0xc000
	ds_read_b128 v[130:133], v168 offset:24592
	global_load_lds_dwordx4 v166, s[66:67]
	v_mfma_f32_32x32x16_bf16 v[18:33], v[212:215], v[224:227], v[18:33]
	s_add_u32 m0, s65, 0xd000
	ds_read_b128 v[138:141], v238 offset:32784
	global_load_lds_dwordx4 v167, s[66:67]
	v_mfma_f32_32x32x16_bf16 v[34:49], v[216:219], v[220:223], v[34:49]
	s_add_u32 m0, s65, 0xe000
	ds_read_b128 v[146:149], v242 offset:24592
	global_load_lds_dwordx4 v166, s[12:13]
	v_mfma_f32_32x32x16_bf16 v[50:65], v[216:219], v[224:227], v[50:65]
	s_add_u32 m0, s65, 0xf000
	ds_read_b128 v[134:137], v169 offset:16
	global_load_lds_dwordx4 v250, s[12:13]
	v_mfma_f32_32x32x16_bf16 v[66:81], v[212:215], v[228:231], v[66:81]
	s_add_u32 m0, s65, 0x10000
	ds_read_b128 v[142:145], v239 offset:8208
	global_load_lds_dwordx4 v166, s[62:63]
	v_mfma_f32_32x32x16_bf16 v[82:97], v[212:215], v[232:235], v[82:97]
	s_add_u32 m0, s65, 0x11000
	ds_read_b128 v[150:153], v243 offset:16
	global_load_lds_dwordx4 v250, s[62:63]
	v_mfma_f32_32x32x16_bf16 v[98:113], v[216:219], v[228:231], v[98:113]
	s_add_u32 s66, s66, 64
	s_addc_u32 s67, s67, 0
	s_add_u32 s12, s12, 64
	s_addc_u32 s13, s13, 0
	v_mfma_f32_32x32x16_bf16 v[114:129], v[216:219], v[232:235], v[114:129]
	s_add_u32 s62, s62, 64
	s_addc_u32 s63, s63, 0
	s_sub_u32 s59, s59, 1
	s_cmp_lg_u32 s59, 0
	s_cbranch_scc1 .Lhw_ffnup_d_loop
	s_waitcnt lgkmcnt(4)
	v_mfma_f32_32x32x16_bf16 v[2:17], v[130:133], v[138:141], v[2:17]
	ds_read_b128 v[212:215], v236 offset:24592
	s_waitcnt lgkmcnt(2)
	v_mfma_f32_32x32x16_bf16 v[18:33], v[130:133], v[142:145], v[18:33]
	ds_read_b128 v[220:223], v240 offset:32784
	v_mfma_f32_32x32x16_bf16 v[34:49], v[134:137], v[138:141], v[34:49]
	ds_read_b128 v[228:231], v244 offset:24592
	v_mfma_f32_32x32x16_bf16 v[50:65], v[134:137], v[142:145], v[50:65]
	ds_read_b128 v[216:219], v237 offset:16
	v_mfma_f32_32x32x16_bf16 v[66:81], v[130:133], v[146:149], v[66:81]
	ds_read_b128 v[224:227], v241 offset:8208
	s_waitcnt lgkmcnt(5)
	v_mfma_f32_32x32x16_bf16 v[82:97], v[130:133], v[150:153], v[82:97]
	ds_read_b128 v[232:235], v245 offset:16
	v_mfma_f32_32x32x16_bf16 v[98:113], v[134:137], v[146:149], v[98:113]
	v_mfma_f32_32x32x16_bf16 v[114:129], v[134:137], v[150:153], v[114:129]
	s_waitcnt vmcnt(0) lgkmcnt(0)
	s_barrier
	v_mfma_f32_32x32x16_bf16 v[2:17], v[212:215], v[220:223], v[2:17]
	ds_read_b128 v[130:133], v169 offset:24592
	v_mfma_f32_32x32x16_bf16 v[18:33], v[212:215], v[224:227], v[18:33]
	ds_read_b128 v[138:141], v239 offset:32784
	v_mfma_f32_32x32x16_bf16 v[34:49], v[216:219], v[220:223], v[34:49]
	ds_read_b128 v[146:149], v243 offset:24592
	v_mfma_f32_32x32x16_bf16 v[50:65], v[216:219], v[224:227], v[50:65]
	ds_read_b128 v[134:137], v168 offset:49168
	v_mfma_f32_32x32x16_bf16 v[66:81], v[212:215], v[228:231], v[66:81]
	ds_read_b128 v[142:145], v238 offset:57360
	v_mfma_f32_32x32x16_bf16 v[82:97], v[212:215], v[232:235], v[82:97]
	ds_read_b128 v[150:153], v242 offset:49168
	v_mfma_f32_32x32x16_bf16 v[98:113], v[216:219], v[228:231], v[98:113]
	v_mfma_f32_32x32x16_bf16 v[114:129], v[216:219], v[232:235], v[114:129]
	s_waitcnt lgkmcnt(4)
	v_mfma_f32_32x32x16_bf16 v[2:17], v[130:133], v[138:141], v[2:17]
	ds_read_b128 v[212:215], v237 offset:24592
	s_waitcnt lgkmcnt(2)
	v_mfma_f32_32x32x16_bf16 v[18:33], v[130:133], v[142:145], v[18:33]
	ds_read_b128 v[220:223], v241 offset:32784
	v_mfma_f32_32x32x16_bf16 v[34:49], v[134:137], v[138:141], v[34:49]
	ds_read_b128 v[228:231], v245 offset:24592
	v_mfma_f32_32x32x16_bf16 v[50:65], v[134:137], v[142:145], v[50:65]
	ds_read_b128 v[216:219], v236 offset:49168
	v_mfma_f32_32x32x16_bf16 v[66:81], v[130:133], v[146:149], v[66:81]
	ds_read_b128 v[224:227], v240 offset:57360
	s_waitcnt lgkmcnt(5)
	v_mfma_f32_32x32x16_bf16 v[82:97], v[130:133], v[150:153], v[82:97]
	ds_read_b128 v[232:235], v244 offset:49168
	v_mfma_f32_32x32x16_bf16 v[98:113], v[134:137], v[146:149], v[98:113]
	v_mfma_f32_32x32x16_bf16 v[114:129], v[134:137], v[150:153], v[114:129]
	s_waitcnt lgkmcnt(0)
	v_mfma_f32_32x32x16_bf16 v[2:17], v[212:215], v[220:223], v[2:17]
	v_mfma_f32_32x32x16_bf16 v[18:33], v[212:215], v[224:227], v[18:33]
	v_mfma_f32_32x32x16_bf16 v[34:49], v[216:219], v[220:223], v[34:49]
	v_mfma_f32_32x32x16_bf16 v[50:65], v[216:219], v[224:227], v[50:65]
	v_mfma_f32_32x32x16_bf16 v[66:81], v[212:215], v[228:231], v[66:81]
	v_mfma_f32_32x32x16_bf16 v[82:97], v[212:215], v[232:235], v[82:97]
	v_mfma_f32_32x32x16_bf16 v[98:113], v[216:219], v[228:231], v[98:113]
	v_mfma_f32_32x32x16_bf16 v[114:129], v[216:219], v[232:235], v[114:129]
	s_nop 7
	s_nop 7
	s_mul_i32 vcc_lo, s6, 0x1600
	s_add_u32 s66, s8, vcc_lo
	s_addc_u32 s67, s9, 0
	s_add_u32 s66, s66, s14
	s_addc_u32 s67, s67, 0
	s_mul_i32 vcc_lo, s6, 0x1600
	s_add_u32 s66, s8, vcc_lo
	s_addc_u32 s67, s9, 0
	s_add_u32 s66, s66, s14
	s_addc_u32 s67, s67, 0
	v_mul_f32_e32 v171, 0xbfb8aa3b, v2
	v_mul_f32_e32 v172, 0xbfb8aa3b, v3
	v_mul_f32_e32 v173, 0xbfb8aa3b, v4
	v_mul_f32_e32 v174, 0xbfb8aa3b, v5
	v_exp_f32_e32 v171, v171
	v_exp_f32_e32 v172, v172
	v_exp_f32_e32 v173, v173
	v_exp_f32_e32 v174, v174
	s_nop 0
	v_add_f32_e32 v171, 1.0, v171
	v_add_f32_e32 v172, 1.0, v172
	v_add_f32_e32 v173, 1.0, v173
	v_add_f32_e32 v174, 1.0, v174
	v_rcp_f32_e32 v171, v171
	v_rcp_f32_e32 v172, v172
	v_rcp_f32_e32 v173, v173
	v_rcp_f32_e32 v174, v174
	s_nop 0
	v_mul_f32_e32 v171, v2, v171
	v_mul_f32_e32 v172, v3, v172
	v_mul_f32_e32 v173, v4, v173
	v_mul_f32_e32 v174, v5, v174
	v_mul_f32_e32 v171, v18, v171
	v_mul_f32_e32 v172, v19, v172
	v_mul_f32_e32 v173, v20, v173
	v_mul_f32_e32 v174, v21, v174
	v_cvt_pk_bf16_f32 v179, v171, v171
	v_cvt_pk_bf16_f32 v180, v172, v172
	v_cvt_pk_bf16_f32 v181, v173, v173
	v_cvt_pk_bf16_f32 v182, v174, v174
	v_mul_f32_e32 v175, 0xbfb8aa3b, v66
	v_mul_f32_e32 v176, 0xbfb8aa3b, v67
	v_mul_f32_e32 v177, 0xbfb8aa3b, v68
	v_mul_f32_e32 v178, 0xbfb8aa3b, v69
	v_exp_f32_e32 v175, v175
	v_exp_f32_e32 v176, v176
	v_exp_f32_e32 v177, v177
	v_exp_f32_e32 v178, v178
	s_nop 0
	v_add_f32_e32 v175, 1.0, v175
	v_add_f32_e32 v176, 1.0, v176
	v_add_f32_e32 v177, 1.0, v177
	v_add_f32_e32 v178, 1.0, v178
	v_rcp_f32_e32 v175, v175
	v_rcp_f32_e32 v176, v176
	v_rcp_f32_e32 v177, v177
	v_rcp_f32_e32 v178, v178
	s_nop 0
	v_mul_f32_e32 v175, v66, v175
	v_mul_f32_e32 v176, v67, v176
	v_mul_f32_e32 v177, v68, v177
	v_mul_f32_e32 v178, v69, v178
	v_mul_f32_e32 v175, v82, v175
	v_mul_f32_e32 v176, v83, v176
	v_mul_f32_e32 v177, v84, v177
	v_mul_f32_e32 v178, v85, v178
	v_cvt_pk_bf16_f32 v183, v175, v175
	v_cvt_pk_bf16_f32 v184, v176, v176
	v_cvt_pk_bf16_f32 v185, v177, v177
	v_cvt_pk_bf16_f32 v186, v178, v178
	s_nop 1
	v_permlane32_swap_b32 v179, v183
	v_permlane32_swap_b32 v180, v184
	v_permlane32_swap_b32 v181, v185
	v_permlane32_swap_b32 v182, v186
	global_store_short v251, v179, s[66:67]
	s_add_u32 s66, s66, 0x1600
	s_addc_u32 s67, s67, 0
	global_store_short v251, v180, s[66:67]
	s_add_u32 s66, s66, 0x1600
	s_addc_u32 s67, s67, 0
	global_store_short v251, v181, s[66:67]
	s_add_u32 s66, s66, 0x1600
	s_addc_u32 s67, s67, 0
	global_store_short v251, v182, s[66:67]
	s_add_u32 s66, s66, 0x1600
	s_addc_u32 s67, s67, 0
	global_store_short v251, v183, s[66:67]
	s_add_u32 s66, s66, 0x1600
	s_addc_u32 s67, s67, 0
	global_store_short v251, v184, s[66:67]
	s_add_u32 s66, s66, 0x1600
	s_addc_u32 s67, s67, 0
	global_store_short v251, v185, s[66:67]
	s_add_u32 s66, s66, 0x1600
	s_addc_u32 s67, s67, 0
	global_store_short v251, v186, s[66:67]
	s_add_u32 s66, s66, 0x1600
	s_addc_u32 s67, s67, 0
	v_mul_f32_e32 v171, 0xbfb8aa3b, v6
	v_mul_f32_e32 v172, 0xbfb8aa3b, v7
	v_mul_f32_e32 v173, 0xbfb8aa3b, v8
	v_mul_f32_e32 v174, 0xbfb8aa3b, v9
	v_exp_f32_e32 v171, v171
	v_exp_f32_e32 v172, v172
	v_exp_f32_e32 v173, v173
	v_exp_f32_e32 v174, v174
	s_nop 0
	v_add_f32_e32 v171, 1.0, v171
	v_add_f32_e32 v172, 1.0, v172
	v_add_f32_e32 v173, 1.0, v173
	v_add_f32_e32 v174, 1.0, v174
	v_rcp_f32_e32 v171, v171
	v_rcp_f32_e32 v172, v172
	v_rcp_f32_e32 v173, v173
	v_rcp_f32_e32 v174, v174
	s_nop 0
	v_mul_f32_e32 v171, v6, v171
	v_mul_f32_e32 v172, v7, v172
	v_mul_f32_e32 v173, v8, v173
	v_mul_f32_e32 v174, v9, v174
	v_mul_f32_e32 v171, v22, v171
	v_mul_f32_e32 v172, v23, v172
	v_mul_f32_e32 v173, v24, v173
	v_mul_f32_e32 v174, v25, v174
	v_cvt_pk_bf16_f32 v179, v171, v171
	v_cvt_pk_bf16_f32 v180, v172, v172
	v_cvt_pk_bf16_f32 v181, v173, v173
	v_cvt_pk_bf16_f32 v182, v174, v174
	v_mul_f32_e32 v175, 0xbfb8aa3b, v70
	v_mul_f32_e32 v176, 0xbfb8aa3b, v71
	v_mul_f32_e32 v177, 0xbfb8aa3b, v72
	v_mul_f32_e32 v178, 0xbfb8aa3b, v73
	v_exp_f32_e32 v175, v175
	v_exp_f32_e32 v176, v176
	v_exp_f32_e32 v177, v177
	v_exp_f32_e32 v178, v178
	s_nop 0
	v_add_f32_e32 v175, 1.0, v175
	v_add_f32_e32 v176, 1.0, v176
	v_add_f32_e32 v177, 1.0, v177
	v_add_f32_e32 v178, 1.0, v178
	v_rcp_f32_e32 v175, v175
	v_rcp_f32_e32 v176, v176
	v_rcp_f32_e32 v177, v177
	v_rcp_f32_e32 v178, v178
	s_nop 0
	v_mul_f32_e32 v175, v70, v175
	v_mul_f32_e32 v176, v71, v176
	v_mul_f32_e32 v177, v72, v177
	v_mul_f32_e32 v178, v73, v178
	v_mul_f32_e32 v175, v86, v175
	v_mul_f32_e32 v176, v87, v176
	v_mul_f32_e32 v177, v88, v177
	v_mul_f32_e32 v178, v89, v178
	v_cvt_pk_bf16_f32 v183, v175, v175
	v_cvt_pk_bf16_f32 v184, v176, v176
	v_cvt_pk_bf16_f32 v185, v177, v177
	v_cvt_pk_bf16_f32 v186, v178, v178
	s_nop 1
	v_permlane32_swap_b32 v179, v183
	v_permlane32_swap_b32 v180, v184
	v_permlane32_swap_b32 v181, v185
	v_permlane32_swap_b32 v182, v186
	global_store_short v251, v179, s[66:67]
	s_add_u32 s66, s66, 0x1600
	s_addc_u32 s67, s67, 0
	global_store_short v251, v180, s[66:67]
	s_add_u32 s66, s66, 0x1600
	s_addc_u32 s67, s67, 0
	global_store_short v251, v181, s[66:67]
	s_add_u32 s66, s66, 0x1600
	s_addc_u32 s67, s67, 0
	global_store_short v251, v182, s[66:67]
	s_add_u32 s66, s66, 0x1600
	s_addc_u32 s67, s67, 0
	global_store_short v251, v183, s[66:67]
	s_add_u32 s66, s66, 0x1600
	s_addc_u32 s67, s67, 0
	global_store_short v251, v184, s[66:67]
	s_add_u32 s66, s66, 0x1600
	s_addc_u32 s67, s67, 0
	global_store_short v251, v185, s[66:67]
	s_add_u32 s66, s66, 0x1600
	s_addc_u32 s67, s67, 0
	global_store_short v251, v186, s[66:67]
	s_add_u32 s66, s66, 0x1600
	s_addc_u32 s67, s67, 0
	v_mul_f32_e32 v171, 0xbfb8aa3b, v10
	v_mul_f32_e32 v172, 0xbfb8aa3b, v11
	v_mul_f32_e32 v173, 0xbfb8aa3b, v12
	v_mul_f32_e32 v174, 0xbfb8aa3b, v13
	v_exp_f32_e32 v171, v171
	v_exp_f32_e32 v172, v172
	v_exp_f32_e32 v173, v173
	v_exp_f32_e32 v174, v174
	s_nop 0
	v_add_f32_e32 v171, 1.0, v171
	v_add_f32_e32 v172, 1.0, v172
	v_add_f32_e32 v173, 1.0, v173
	v_add_f32_e32 v174, 1.0, v174
	v_rcp_f32_e32 v171, v171
	v_rcp_f32_e32 v172, v172
	v_rcp_f32_e32 v173, v173
	v_rcp_f32_e32 v174, v174
	s_nop 0
	v_mul_f32_e32 v171, v10, v171
	v_mul_f32_e32 v172, v11, v172
	v_mul_f32_e32 v173, v12, v173
	v_mul_f32_e32 v174, v13, v174
	v_mul_f32_e32 v171, v26, v171
	v_mul_f32_e32 v172, v27, v172
	v_mul_f32_e32 v173, v28, v173
	v_mul_f32_e32 v174, v29, v174
	v_cvt_pk_bf16_f32 v179, v171, v171
	v_cvt_pk_bf16_f32 v180, v172, v172
	v_cvt_pk_bf16_f32 v181, v173, v173
	v_cvt_pk_bf16_f32 v182, v174, v174
	v_mul_f32_e32 v175, 0xbfb8aa3b, v74
	v_mul_f32_e32 v176, 0xbfb8aa3b, v75
	v_mul_f32_e32 v177, 0xbfb8aa3b, v76
	v_mul_f32_e32 v178, 0xbfb8aa3b, v77
	v_exp_f32_e32 v175, v175
	v_exp_f32_e32 v176, v176
	v_exp_f32_e32 v177, v177
	v_exp_f32_e32 v178, v178
	s_nop 0
	v_add_f32_e32 v175, 1.0, v175
	v_add_f32_e32 v176, 1.0, v176
	v_add_f32_e32 v177, 1.0, v177
	v_add_f32_e32 v178, 1.0, v178
	v_rcp_f32_e32 v175, v175
	v_rcp_f32_e32 v176, v176
	v_rcp_f32_e32 v177, v177
	v_rcp_f32_e32 v178, v178
	s_nop 0
	v_mul_f32_e32 v175, v74, v175
	v_mul_f32_e32 v176, v75, v176
	v_mul_f32_e32 v177, v76, v177
	v_mul_f32_e32 v178, v77, v178
	v_mul_f32_e32 v175, v90, v175
	v_mul_f32_e32 v176, v91, v176
	v_mul_f32_e32 v177, v92, v177
	v_mul_f32_e32 v178, v93, v178
	v_cvt_pk_bf16_f32 v183, v175, v175
	v_cvt_pk_bf16_f32 v184, v176, v176
	v_cvt_pk_bf16_f32 v185, v177, v177
	v_cvt_pk_bf16_f32 v186, v178, v178
	s_nop 1
	v_permlane32_swap_b32 v179, v183
	v_permlane32_swap_b32 v180, v184
	v_permlane32_swap_b32 v181, v185
	v_permlane32_swap_b32 v182, v186
	global_store_short v251, v179, s[66:67]
	s_add_u32 s66, s66, 0x1600
	s_addc_u32 s67, s67, 0
	global_store_short v251, v180, s[66:67]
	s_add_u32 s66, s66, 0x1600
	s_addc_u32 s67, s67, 0
	global_store_short v251, v181, s[66:67]
	s_add_u32 s66, s66, 0x1600
	s_addc_u32 s67, s67, 0
	global_store_short v251, v182, s[66:67]
	s_add_u32 s66, s66, 0x1600
	s_addc_u32 s67, s67, 0
	global_store_short v251, v183, s[66:67]
	s_add_u32 s66, s66, 0x1600
	s_addc_u32 s67, s67, 0
	global_store_short v251, v184, s[66:67]
	s_add_u32 s66, s66, 0x1600
	s_addc_u32 s67, s67, 0
	global_store_short v251, v185, s[66:67]
	s_add_u32 s66, s66, 0x1600
	s_addc_u32 s67, s67, 0
	global_store_short v251, v186, s[66:67]
	s_add_u32 s66, s66, 0x1600
	s_addc_u32 s67, s67, 0
	v_mul_f32_e32 v171, 0xbfb8aa3b, v14
	v_mul_f32_e32 v172, 0xbfb8aa3b, v15
	v_mul_f32_e32 v173, 0xbfb8aa3b, v16
	v_mul_f32_e32 v174, 0xbfb8aa3b, v17
	v_exp_f32_e32 v171, v171
	v_exp_f32_e32 v172, v172
	v_exp_f32_e32 v173, v173
	v_exp_f32_e32 v174, v174
	s_nop 0
	v_add_f32_e32 v171, 1.0, v171
	v_add_f32_e32 v172, 1.0, v172
	v_add_f32_e32 v173, 1.0, v173
	v_add_f32_e32 v174, 1.0, v174
	v_rcp_f32_e32 v171, v171
	v_rcp_f32_e32 v172, v172
	v_rcp_f32_e32 v173, v173
	v_rcp_f32_e32 v174, v174
	s_nop 0
	v_mul_f32_e32 v171, v14, v171
	v_mul_f32_e32 v172, v15, v172
	v_mul_f32_e32 v173, v16, v173
	v_mul_f32_e32 v174, v17, v174
	v_mul_f32_e32 v171, v30, v171
	v_mul_f32_e32 v172, v31, v172
	v_mul_f32_e32 v173, v32, v173
	v_mul_f32_e32 v174, v33, v174
	v_cvt_pk_bf16_f32 v179, v171, v171
	v_cvt_pk_bf16_f32 v180, v172, v172
	v_cvt_pk_bf16_f32 v181, v173, v173
	v_cvt_pk_bf16_f32 v182, v174, v174
	v_mul_f32_e32 v175, 0xbfb8aa3b, v78
	v_mul_f32_e32 v176, 0xbfb8aa3b, v79
	v_mul_f32_e32 v177, 0xbfb8aa3b, v80
	v_mul_f32_e32 v178, 0xbfb8aa3b, v81
	v_exp_f32_e32 v175, v175
	v_exp_f32_e32 v176, v176
	v_exp_f32_e32 v177, v177
	v_exp_f32_e32 v178, v178
	s_nop 0
	v_add_f32_e32 v175, 1.0, v175
	v_add_f32_e32 v176, 1.0, v176
	v_add_f32_e32 v177, 1.0, v177
	v_add_f32_e32 v178, 1.0, v178
	v_rcp_f32_e32 v175, v175
	v_rcp_f32_e32 v176, v176
	v_rcp_f32_e32 v177, v177
	v_rcp_f32_e32 v178, v178
	s_nop 0
	v_mul_f32_e32 v175, v78, v175
	v_mul_f32_e32 v176, v79, v176
	v_mul_f32_e32 v177, v80, v177
	v_mul_f32_e32 v178, v81, v178
	v_mul_f32_e32 v175, v94, v175
	v_mul_f32_e32 v176, v95, v176
	v_mul_f32_e32 v177, v96, v177
	v_mul_f32_e32 v178, v97, v178
	v_cvt_pk_bf16_f32 v183, v175, v175
	v_cvt_pk_bf16_f32 v184, v176, v176
	v_cvt_pk_bf16_f32 v185, v177, v177
	v_cvt_pk_bf16_f32 v186, v178, v178
	s_nop 1
	v_permlane32_swap_b32 v179, v183
	v_permlane32_swap_b32 v180, v184
	v_permlane32_swap_b32 v181, v185
	v_permlane32_swap_b32 v182, v186
	global_store_short v251, v179, s[66:67]
	s_add_u32 s66, s66, 0x1600
	s_addc_u32 s67, s67, 0
	global_store_short v251, v180, s[66:67]
	s_add_u32 s66, s66, 0x1600
	s_addc_u32 s67, s67, 0
	global_store_short v251, v181, s[66:67]
	s_add_u32 s66, s66, 0x1600
	s_addc_u32 s67, s67, 0
	global_store_short v251, v182, s[66:67]
	s_add_u32 s66, s66, 0x1600
	s_addc_u32 s67, s67, 0
	global_store_short v251, v183, s[66:67]
	s_add_u32 s66, s66, 0x1600
	s_addc_u32 s67, s67, 0
	global_store_short v251, v184, s[66:67]
	s_add_u32 s66, s66, 0x1600
	s_addc_u32 s67, s67, 0
	global_store_short v251, v185, s[66:67]
	s_add_u32 s66, s66, 0x1600
	s_addc_u32 s67, s67, 0
	global_store_short v251, v186, s[66:67]
	s_add_u32 s66, s66, 0x1600
	s_addc_u32 s67, s67, 0
	v_mul_f32_e32 v171, 0xbfb8aa3b, v34
	v_mul_f32_e32 v172, 0xbfb8aa3b, v35
	v_mul_f32_e32 v173, 0xbfb8aa3b, v36
	v_mul_f32_e32 v174, 0xbfb8aa3b, v37
	v_exp_f32_e32 v171, v171
	v_exp_f32_e32 v172, v172
	v_exp_f32_e32 v173, v173
	v_exp_f32_e32 v174, v174
	s_nop 0
	v_add_f32_e32 v171, 1.0, v171
	v_add_f32_e32 v172, 1.0, v172
	v_add_f32_e32 v173, 1.0, v173
	v_add_f32_e32 v174, 1.0, v174
	v_rcp_f32_e32 v171, v171
	v_rcp_f32_e32 v172, v172
	v_rcp_f32_e32 v173, v173
	v_rcp_f32_e32 v174, v174
	s_nop 0
	v_mul_f32_e32 v171, v34, v171
	v_mul_f32_e32 v172, v35, v172
	v_mul_f32_e32 v173, v36, v173
	v_mul_f32_e32 v174, v37, v174
	v_mul_f32_e32 v171, v50, v171
	v_mul_f32_e32 v172, v51, v172
	v_mul_f32_e32 v173, v52, v173
	v_mul_f32_e32 v174, v53, v174
	v_cvt_pk_bf16_f32 v179, v171, v171
	v_cvt_pk_bf16_f32 v180, v172, v172
	v_cvt_pk_bf16_f32 v181, v173, v173
	v_cvt_pk_bf16_f32 v182, v174, v174
	v_mul_f32_e32 v175, 0xbfb8aa3b, v98
	v_mul_f32_e32 v176, 0xbfb8aa3b, v99
	v_mul_f32_e32 v177, 0xbfb8aa3b, v100
	v_mul_f32_e32 v178, 0xbfb8aa3b, v101
	v_exp_f32_e32 v175, v175
	v_exp_f32_e32 v176, v176
	v_exp_f32_e32 v177, v177
	v_exp_f32_e32 v178, v178
	s_nop 0
	v_add_f32_e32 v175, 1.0, v175
	v_add_f32_e32 v176, 1.0, v176
	v_add_f32_e32 v177, 1.0, v177
	v_add_f32_e32 v178, 1.0, v178
	v_rcp_f32_e32 v175, v175
	v_rcp_f32_e32 v176, v176
	v_rcp_f32_e32 v177, v177
	v_rcp_f32_e32 v178, v178
	s_nop 0
	v_mul_f32_e32 v175, v98, v175
	v_mul_f32_e32 v176, v99, v176
	v_mul_f32_e32 v177, v100, v177
	v_mul_f32_e32 v178, v101, v178
	v_mul_f32_e32 v175, v114, v175
	v_mul_f32_e32 v176, v115, v176
	v_mul_f32_e32 v177, v116, v177
	v_mul_f32_e32 v178, v117, v178
	v_cvt_pk_bf16_f32 v183, v175, v175
	v_cvt_pk_bf16_f32 v184, v176, v176
	v_cvt_pk_bf16_f32 v185, v177, v177
	v_cvt_pk_bf16_f32 v186, v178, v178
	s_nop 1
	v_permlane32_swap_b32 v179, v183
	v_permlane32_swap_b32 v180, v184
	v_permlane32_swap_b32 v181, v185
	v_permlane32_swap_b32 v182, v186
	global_store_short v251, v179, s[66:67]
	s_add_u32 s66, s66, 0x1600
	s_addc_u32 s67, s67, 0
	global_store_short v251, v180, s[66:67]
	s_add_u32 s66, s66, 0x1600
	s_addc_u32 s67, s67, 0
	global_store_short v251, v181, s[66:67]
	s_add_u32 s66, s66, 0x1600
	s_addc_u32 s67, s67, 0
	global_store_short v251, v182, s[66:67]
	s_add_u32 s66, s66, 0x1600
	s_addc_u32 s67, s67, 0
	global_store_short v251, v183, s[66:67]
	s_add_u32 s66, s66, 0x1600
	s_addc_u32 s67, s67, 0
	global_store_short v251, v184, s[66:67]
	s_add_u32 s66, s66, 0x1600
	s_addc_u32 s67, s67, 0
	global_store_short v251, v185, s[66:67]
	s_add_u32 s66, s66, 0x1600
	s_addc_u32 s67, s67, 0
	global_store_short v251, v186, s[66:67]
	s_add_u32 s66, s66, 0x1600
	s_addc_u32 s67, s67, 0
	v_mul_f32_e32 v171, 0xbfb8aa3b, v38
	v_mul_f32_e32 v172, 0xbfb8aa3b, v39
	v_mul_f32_e32 v173, 0xbfb8aa3b, v40
	v_mul_f32_e32 v174, 0xbfb8aa3b, v41
	v_exp_f32_e32 v171, v171
	v_exp_f32_e32 v172, v172
	v_exp_f32_e32 v173, v173
	v_exp_f32_e32 v174, v174
	s_nop 0
	v_add_f32_e32 v171, 1.0, v171
	v_add_f32_e32 v172, 1.0, v172
	v_add_f32_e32 v173, 1.0, v173
	v_add_f32_e32 v174, 1.0, v174
	v_rcp_f32_e32 v171, v171
	v_rcp_f32_e32 v172, v172
	v_rcp_f32_e32 v173, v173
	v_rcp_f32_e32 v174, v174
	s_nop 0
	v_mul_f32_e32 v171, v38, v171
	v_mul_f32_e32 v172, v39, v172
	v_mul_f32_e32 v173, v40, v173
	v_mul_f32_e32 v174, v41, v174
	v_mul_f32_e32 v171, v54, v171
	v_mul_f32_e32 v172, v55, v172
	v_mul_f32_e32 v173, v56, v173
	v_mul_f32_e32 v174, v57, v174
	v_cvt_pk_bf16_f32 v179, v171, v171
	v_cvt_pk_bf16_f32 v180, v172, v172
	v_cvt_pk_bf16_f32 v181, v173, v173
	v_cvt_pk_bf16_f32 v182, v174, v174
	v_mul_f32_e32 v175, 0xbfb8aa3b, v102
	v_mul_f32_e32 v176, 0xbfb8aa3b, v103
	v_mul_f32_e32 v177, 0xbfb8aa3b, v104
	v_mul_f32_e32 v178, 0xbfb8aa3b, v105
	v_exp_f32_e32 v175, v175
	v_exp_f32_e32 v176, v176
	v_exp_f32_e32 v177, v177
	v_exp_f32_e32 v178, v178
	s_nop 0
	v_add_f32_e32 v175, 1.0, v175
	v_add_f32_e32 v176, 1.0, v176
	v_add_f32_e32 v177, 1.0, v177
	v_add_f32_e32 v178, 1.0, v178
	v_rcp_f32_e32 v175, v175
	v_rcp_f32_e32 v176, v176
	v_rcp_f32_e32 v177, v177
	v_rcp_f32_e32 v178, v178
	s_nop 0
	v_mul_f32_e32 v175, v102, v175
	v_mul_f32_e32 v176, v103, v176
	v_mul_f32_e32 v177, v104, v177
	v_mul_f32_e32 v178, v105, v178
	v_mul_f32_e32 v175, v118, v175
	v_mul_f32_e32 v176, v119, v176
	v_mul_f32_e32 v177, v120, v177
	v_mul_f32_e32 v178, v121, v178
	v_cvt_pk_bf16_f32 v183, v175, v175
	v_cvt_pk_bf16_f32 v184, v176, v176
	v_cvt_pk_bf16_f32 v185, v177, v177
	v_cvt_pk_bf16_f32 v186, v178, v178
	s_nop 1
	v_permlane32_swap_b32 v179, v183
	v_permlane32_swap_b32 v180, v184
	v_permlane32_swap_b32 v181, v185
	v_permlane32_swap_b32 v182, v186
	global_store_short v251, v179, s[66:67]
	s_add_u32 s66, s66, 0x1600
	s_addc_u32 s67, s67, 0
	global_store_short v251, v180, s[66:67]
	s_add_u32 s66, s66, 0x1600
	s_addc_u32 s67, s67, 0
	global_store_short v251, v181, s[66:67]
	s_add_u32 s66, s66, 0x1600
	s_addc_u32 s67, s67, 0
	global_store_short v251, v182, s[66:67]
	s_add_u32 s66, s66, 0x1600
	s_addc_u32 s67, s67, 0
	global_store_short v251, v183, s[66:67]
	s_add_u32 s66, s66, 0x1600
	s_addc_u32 s67, s67, 0
	global_store_short v251, v184, s[66:67]
	s_add_u32 s66, s66, 0x1600
	s_addc_u32 s67, s67, 0
	global_store_short v251, v185, s[66:67]
	s_add_u32 s66, s66, 0x1600
	s_addc_u32 s67, s67, 0
	global_store_short v251, v186, s[66:67]
	s_add_u32 s66, s66, 0x1600
	s_addc_u32 s67, s67, 0
	v_mul_f32_e32 v171, 0xbfb8aa3b, v42
	v_mul_f32_e32 v172, 0xbfb8aa3b, v43
	v_mul_f32_e32 v173, 0xbfb8aa3b, v44
	v_mul_f32_e32 v174, 0xbfb8aa3b, v45
	v_exp_f32_e32 v171, v171
	v_exp_f32_e32 v172, v172
	v_exp_f32_e32 v173, v173
	v_exp_f32_e32 v174, v174
	s_nop 0
	v_add_f32_e32 v171, 1.0, v171
	v_add_f32_e32 v172, 1.0, v172
	v_add_f32_e32 v173, 1.0, v173
	v_add_f32_e32 v174, 1.0, v174
	v_rcp_f32_e32 v171, v171
	v_rcp_f32_e32 v172, v172
	v_rcp_f32_e32 v173, v173
	v_rcp_f32_e32 v174, v174
	s_nop 0
	v_mul_f32_e32 v171, v42, v171
	v_mul_f32_e32 v172, v43, v172
	v_mul_f32_e32 v173, v44, v173
	v_mul_f32_e32 v174, v45, v174
	v_mul_f32_e32 v171, v58, v171
	v_mul_f32_e32 v172, v59, v172
	v_mul_f32_e32 v173, v60, v173
	v_mul_f32_e32 v174, v61, v174
	v_cvt_pk_bf16_f32 v179, v171, v171
	v_cvt_pk_bf16_f32 v180, v172, v172
	v_cvt_pk_bf16_f32 v181, v173, v173
	v_cvt_pk_bf16_f32 v182, v174, v174
	v_mul_f32_e32 v175, 0xbfb8aa3b, v106
	v_mul_f32_e32 v176, 0xbfb8aa3b, v107
	v_mul_f32_e32 v177, 0xbfb8aa3b, v108
	v_mul_f32_e32 v178, 0xbfb8aa3b, v109
	v_exp_f32_e32 v175, v175
	v_exp_f32_e32 v176, v176
	v_exp_f32_e32 v177, v177
	v_exp_f32_e32 v178, v178
	s_nop 0
	v_add_f32_e32 v175, 1.0, v175
	v_add_f32_e32 v176, 1.0, v176
	v_add_f32_e32 v177, 1.0, v177
	v_add_f32_e32 v178, 1.0, v178
	v_rcp_f32_e32 v175, v175
	v_rcp_f32_e32 v176, v176
	v_rcp_f32_e32 v177, v177
	v_rcp_f32_e32 v178, v178
	s_nop 0
	v_mul_f32_e32 v175, v106, v175
	v_mul_f32_e32 v176, v107, v176
	v_mul_f32_e32 v177, v108, v177
	v_mul_f32_e32 v178, v109, v178
	v_mul_f32_e32 v175, v122, v175
	v_mul_f32_e32 v176, v123, v176
	v_mul_f32_e32 v177, v124, v177
	v_mul_f32_e32 v178, v125, v178
	v_cvt_pk_bf16_f32 v183, v175, v175
	v_cvt_pk_bf16_f32 v184, v176, v176
	v_cvt_pk_bf16_f32 v185, v177, v177
	v_cvt_pk_bf16_f32 v186, v178, v178
	s_nop 1
	v_permlane32_swap_b32 v179, v183
	v_permlane32_swap_b32 v180, v184
	v_permlane32_swap_b32 v181, v185
	v_permlane32_swap_b32 v182, v186
	global_store_short v251, v179, s[66:67]
	s_add_u32 s66, s66, 0x1600
	s_addc_u32 s67, s67, 0
	global_store_short v251, v180, s[66:67]
	s_add_u32 s66, s66, 0x1600
	s_addc_u32 s67, s67, 0
	global_store_short v251, v181, s[66:67]
	s_add_u32 s66, s66, 0x1600
	s_addc_u32 s67, s67, 0
	global_store_short v251, v182, s[66:67]
	s_add_u32 s66, s66, 0x1600
	s_addc_u32 s67, s67, 0
	global_store_short v251, v183, s[66:67]
	s_add_u32 s66, s66, 0x1600
	s_addc_u32 s67, s67, 0
	global_store_short v251, v184, s[66:67]
	s_add_u32 s66, s66, 0x1600
	s_addc_u32 s67, s67, 0
	global_store_short v251, v185, s[66:67]
	s_add_u32 s66, s66, 0x1600
	s_addc_u32 s67, s67, 0
	global_store_short v251, v186, s[66:67]
	s_add_u32 s66, s66, 0x1600
	s_addc_u32 s67, s67, 0
	v_mul_f32_e32 v171, 0xbfb8aa3b, v46
	v_mul_f32_e32 v172, 0xbfb8aa3b, v47
	v_mul_f32_e32 v173, 0xbfb8aa3b, v48
	v_mul_f32_e32 v174, 0xbfb8aa3b, v49
	v_exp_f32_e32 v171, v171
	v_exp_f32_e32 v172, v172
	v_exp_f32_e32 v173, v173
	v_exp_f32_e32 v174, v174
	s_nop 0
	v_add_f32_e32 v171, 1.0, v171
	v_add_f32_e32 v172, 1.0, v172
	v_add_f32_e32 v173, 1.0, v173
	v_add_f32_e32 v174, 1.0, v174
	v_rcp_f32_e32 v171, v171
	v_rcp_f32_e32 v172, v172
	v_rcp_f32_e32 v173, v173
	v_rcp_f32_e32 v174, v174
	s_nop 0
	v_mul_f32_e32 v171, v46, v171
	v_mul_f32_e32 v172, v47, v172
	v_mul_f32_e32 v173, v48, v173
	v_mul_f32_e32 v174, v49, v174
	v_mul_f32_e32 v171, v62, v171
	v_mul_f32_e32 v172, v63, v172
	v_mul_f32_e32 v173, v64, v173
	v_mul_f32_e32 v174, v65, v174
	v_cvt_pk_bf16_f32 v179, v171, v171
	v_cvt_pk_bf16_f32 v180, v172, v172
	v_cvt_pk_bf16_f32 v181, v173, v173
	v_cvt_pk_bf16_f32 v182, v174, v174
	v_mul_f32_e32 v175, 0xbfb8aa3b, v110
	v_mul_f32_e32 v176, 0xbfb8aa3b, v111
	v_mul_f32_e32 v177, 0xbfb8aa3b, v112
	v_mul_f32_e32 v178, 0xbfb8aa3b, v113
	v_exp_f32_e32 v175, v175
	v_exp_f32_e32 v176, v176
	v_exp_f32_e32 v177, v177
	v_exp_f32_e32 v178, v178
	s_nop 0
	v_add_f32_e32 v175, 1.0, v175
	v_add_f32_e32 v176, 1.0, v176
	v_add_f32_e32 v177, 1.0, v177
	v_add_f32_e32 v178, 1.0, v178
	v_rcp_f32_e32 v175, v175
	v_rcp_f32_e32 v176, v176
	v_rcp_f32_e32 v177, v177
	v_rcp_f32_e32 v178, v178
	s_nop 0
	v_mul_f32_e32 v175, v110, v175
	v_mul_f32_e32 v176, v111, v176
	v_mul_f32_e32 v177, v112, v177
	v_mul_f32_e32 v178, v113, v178
	v_mul_f32_e32 v175, v126, v175
	v_mul_f32_e32 v176, v127, v176
	v_mul_f32_e32 v177, v128, v177
	v_mul_f32_e32 v178, v129, v178
	v_cvt_pk_bf16_f32 v183, v175, v175
	v_cvt_pk_bf16_f32 v184, v176, v176
	v_cvt_pk_bf16_f32 v185, v177, v177
	v_cvt_pk_bf16_f32 v186, v178, v178
	s_nop 1
	v_permlane32_swap_b32 v179, v183
	v_permlane32_swap_b32 v180, v184
	v_permlane32_swap_b32 v181, v185
	v_permlane32_swap_b32 v182, v186
	global_store_short v251, v179, s[66:67]
	s_add_u32 s66, s66, 0x1600
	s_addc_u32 s67, s67, 0
	global_store_short v251, v180, s[66:67]
	s_add_u32 s66, s66, 0x1600
	s_addc_u32 s67, s67, 0
	global_store_short v251, v181, s[66:67]
	s_add_u32 s66, s66, 0x1600
	s_addc_u32 s67, s67, 0
	global_store_short v251, v182, s[66:67]
	s_add_u32 s66, s66, 0x1600
	s_addc_u32 s67, s67, 0
	global_store_short v251, v183, s[66:67]
	s_add_u32 s66, s66, 0x1600
	s_addc_u32 s67, s67, 0
	global_store_short v251, v184, s[66:67]
	s_add_u32 s66, s66, 0x1600
	s_addc_u32 s67, s67, 0
	global_store_short v251, v185, s[66:67]
	s_add_u32 s66, s66, 0x1600
	s_addc_u32 s67, s67, 0
	global_store_short v251, v186, s[66:67]
	s_add_u32 s66, s66, 0x1600
	s_addc_u32 s67, s67, 0
	v_readlane_b32 s62, v246, 14
	s_nop 0
	s_add_i32 s2, s2, s62
	s_branch .Lhw_ffnup_dloop
